# speedup vs baseline: 1.0083x; 1.0040x over previous
; __device__ __forceinline__ int mytid(int wv) { return (wv << 6) | (int)__builtin_amdgcn_mbcnt_hi(~0u, __builtin_amdgcn_mbcnt_lo(~0u, 0u)); }
; #define p getp()
; template <int MODE>
; __device__ __forceinline__ void rms_rows(KP p, const float* __restrict__ g, int wv) {
;   int tid = mytid(wv); asm volatile("" : "+v"(tid));
;   const int wid = tid >> 6, lane = tid & 63;
;   for (int row = blockIdx.x * 8 + wid; row < TOK; row += gridDim.x * 8) {
;     const float* src;
;     if (MODE == 0) src = (row < SEQ) ? p->x_prompt + (long)row * DM : p->x_sample + (long)(row - SEQ) * DM;
;     else src = p->X + (long)row * DM;
;     f32x4 v[8];
; #pragma unroll
;     for (int i = 0; i < 8; ++i) v[i] = *reinterpret_cast<const f32x4*>(src + (i * 64 + lane) * 4);
;     float ss = 0.f;
; #pragma unroll
;     for (int i = 0; i < 8; ++i) ss += v[i][0] * v[i][0] + v[i][1] * v[i][1] + v[i][2] * v[i][2] + v[i][3] * v[i][3];
;     ss = wave_sum(ss);
;     const float rstd = rsqrtf(ss * (1.f / DM) + 1e-6f);
.LBB0_67:
	v_mov_b32_e32 v2, v192
	v_readlane_b32 s0, v255, 8
	v_ashrrev_i32_e32 v6, 6, v2
	v_xor_b32_e32 v206, 32, v200
	v_add_u32_e32 v74, s0, v6
	s_mov_b32 s0, 0xc000
	v_cmp_gt_i32_e32 vcc, s0, v74
	v_xor_b32_e32 v201, 2, v200
	s_and_saveexec_b64 s[4:5], vcc
	s_cbranch_execz .LBB0_70
	s_load_dwordx2 s[6:7], s[14:15], 0x10
	v_lshlrev_b32_e32 v7, 2, v2
	v_and_b32_e32 v8, 0xfc, v7
	v_and_b32_e32 v2, 64, v200
	v_lshlrev_b32_e32 v34, 2, v8
	v_add_u32_e32 v9, 64, v2
	s_waitcnt lgkmcnt(0)
	global_load_dwordx4 v[2:5], v34, s[6:7]
	v_cmp_lt_i32_e32 vcc, v206, v9
	s_mov_b32 s0, 0x1c000
	v_mov_b32_e32 v35, 0
	v_cndmask_b32_e32 v10, v200, v206, vcc
	v_lshlrev_b32_e32 v75, 2, v10
	v_xor_b32_e32 v10, 16, v200
	v_cmp_lt_i32_e32 vcc, v10, v9
	v_or_b32_e32 v12, 0x400, v8
	v_lshl_add_u64 v[36:37], s[6:7], 0, v[34:35]
	v_cndmask_b32_e32 v10, v200, v10, vcc
	v_lshlrev_b32_e32 v76, 2, v10
	v_xor_b32_e32 v10, 8, v200
	v_cmp_lt_i32_e32 vcc, v10, v9
	v_or_b32_e32 v14, 0x500, v8
	v_lshlrev_b32_e32 v34, 2, v12
	v_cndmask_b32_e32 v10, v200, v10, vcc
	v_lshlrev_b32_e32 v77, 2, v10
	v_xor_b32_e32 v10, 4, v200
	v_cmp_lt_i32_e32 vcc, v10, v9
	v_or_b32_e32 v16, 0x600, v8
	v_lshl_add_u64 v[38:39], s[6:7], 0, v[34:35]
	v_cndmask_b32_e32 v10, v200, v10, vcc
	v_cmp_lt_i32_e32 vcc, v201, v9
	v_lshlrev_b32_e32 v78, 2, v10
	v_lshlrev_b32_e32 v34, 2, v14
	v_cndmask_b32_e32 v10, v200, v201, vcc
	v_lshlrev_b32_e32 v79, 2, v10
	v_xor_b32_e32 v10, 1, v200
	v_cmp_lt_i32_e32 vcc, v10, v9
	v_or_b32_e32 v18, 0x700, v8
	v_lshl_add_u64 v[40:41], s[6:7], 0, v[34:35]
	v_cndmask_b32_e32 v9, v200, v10, vcc
	v_lshlrev_b32_e32 v80, 2, v9
	v_and_b32_e32 v10, 60, v7
	v_lshlrev_b32_e32 v7, 8, v8
	v_mov_b32_e32 v9, 0x10000
	v_bitop3_b32 v22, v7, s0, v9 bitop3:0xc8
	s_mov_b32 s0, 0x2c000
	v_mov_b32_e32 v9, 0x20000
	v_bitop3_b32 v24, v7, s0, v9 bitop3:0xc8
	s_mov_b32 s0, 0x3c000
	v_mov_b32_e32 v9, 0x30000
	v_and_b32_e32 v20, 0xc000, v7
	v_bitop3_b32 v26, v7, s0, v9 bitop3:0xc8
	v_lshlrev_b32_e32 v7, 8, v12
	v_and_b32_e32 v28, 0x4c000, v7
	v_lshlrev_b32_e32 v7, 8, v14
	v_and_b32_e32 v30, 0x5c000, v7
	v_lshlrev_b32_e32 v34, 2, v16
	v_lshlrev_b32_e32 v7, 8, v16
	v_lshl_add_u64 v[42:43], s[6:7], 0, v[34:35]
	v_and_b32_e32 v32, 0x6c000, v7
	v_lshlrev_b32_e32 v34, 2, v18
	v_lshlrev_b32_e32 v7, 8, v18
	v_lshl_add_u64 v[44:45], s[6:7], 0, v[34:35]
	v_and_b32_e32 v34, 0x7c000, v7
	v_readlane_b32 s1, v255, 7
	s_lshl_b32 s0, s88, 3
	s_mov_b64 s[6:7], 0
	v_lshl_add_u32 v81, v6, 6, s1
	s_movk_i32 s1, 0x4000
	v_lshlrev_b32_e32 v46, 2, v8
	v_lshlrev_b32_e32 v48, 2, v12
	v_lshlrev_b32_e32 v50, 2, v14
	v_lshlrev_b32_e32 v52, 2, v16
	v_lshlrev_b32_e32 v54, 2, v18
	v_mov_b32_e32 v82, 0x358637bd
	s_mov_b32 s3, 0x800000
	s_mov_b64 s[8:9], 0xba40000
	v_lshlrev_b32_e32 v56, 1, v20
	v_lshlrev_b32_e32 v58, 1, v10
	v_lshlrev_b32_e32 v60, 1, v22
	v_lshlrev_b32_e32 v62, 1, v24
	v_lshlrev_b32_e32 v64, 1, v26
	v_lshlrev_b32_e32 v66, 1, v28
	v_lshlrev_b32_e32 v68, 1, v30
	v_lshlrev_b32_e32 v70, 1, v32
	v_lshlrev_b32_e32 v72, 1, v34
	s_mov_b32 s10, 0xbfff
	v_mov_b32_e32 v47, v35
	v_mov_b32_e32 v49, v35
	v_mov_b32_e32 v51, v35
	v_mov_b32_e32 v53, v35
	v_mov_b32_e32 v55, v35
	global_load_dwordx4 v[144:147], v[36:37], off offset:1024
	global_load_dwordx4 v[148:151], v[36:37], off offset:2048
	global_load_dwordx4 v[152:155], v[36:37], off offset:3072
	global_load_dwordx4 v[156:159], v[38:39], off
	global_load_dwordx4 v[160:163], v[40:41], off
	global_load_dwordx4 v[164:167], v[42:43], off
	global_load_dwordx4 v[168:171], v[44:45], off
.LBB0_69:
	v_cmp_gt_i32_e32 vcc, s1, v74
	v_add_u32_e32 v6, 0xffffc000, v74
	v_ashrrev_i32_e32 v7, 31, v74
	v_cndmask_b32_e64 v34, 8, 0, vcc
	v_lshl_add_u64 v[8:9], s[14:15], 0, v[34:35]
	global_load_dwordx2 v[8:9], v[8:9], off
	v_cndmask_b32_e32 v7, 0, v7, vcc
	v_cndmask_b32_e32 v6, v6, v74, vcc
	v_lshlrev_b64 v[6:7], 13, v[6:7]
	v_mov_b32_e32 v65, v35
	v_mov_b32_e32 v67, v35
	v_mov_b32_e32 v69, v35
	v_mov_b32_e32 v71, v35
	v_mov_b32_e32 v73, v35
	s_waitcnt vmcnt(0)
	v_lshl_add_u64 v[6:7], v[8:9], 0, v[6:7]
	v_lshl_add_u64 v[88:89], v[6:7], 0, v[48:49]
	v_lshl_add_u64 v[90:91], v[6:7], 0, v[50:51]
	v_lshl_add_u64 v[92:93], v[6:7], 0, v[52:53]
	v_lshl_add_u64 v[94:95], v[6:7], 0, v[54:55]
	v_lshl_add_u64 v[96:97], v[6:7], 0, v[46:47]
	global_load_dwordx4 v[18:21], v[88:89], off
	global_load_dwordx4 v[14:17], v[90:91], off
	global_load_dwordx4 v[10:13], v[92:93], off
	global_load_dwordx4 v[6:9], v[94:95], off
	global_load_dwordx4 v[84:87], v[96:97], off
	global_load_dwordx4 v[30:33], v[96:97], off offset:1024
	global_load_dwordx4 v[26:29], v[96:97], off offset:2048
	global_load_dwordx4 v[22:25], v[96:97], off offset:3072
	s_waitcnt vmcnt(7)
	v_mov_b32_e32 v90, v19
	s_waitcnt vmcnt(6)
	v_mov_b32_e32 v91, v15
	v_mov_b32_e32 v88, v18
	v_mov_b32_e32 v89, v14
	s_waitcnt vmcnt(3)
	v_mul_f32_e32 v34, v85, v85
	s_waitcnt vmcnt(2)
	v_mul_f32_e32 v57, v31, v31
	s_waitcnt vmcnt(1)
	v_mul_f32_e32 v59, v27, v27
	v_fmac_f32_e32 v34, v84, v84
	v_fmac_f32_e32 v57, v30, v30
	s_waitcnt vmcnt(0)
; __device__ __forceinline__ long ablk(int row, int col, int nkt) { return ((long)(row >> 8) * nkt + (col >> 6)) * 16384 + (row & 255) * 64 + (col & 63); }
; #define p getp()
; template <int MODE>
; __device__ __forceinline__ void rms_rows(KP p, const float* __restrict__ g, int wv) {
;     ...
;     float ss = 0.f;
; #pragma unroll
;     for (int i = 0; i < 8; ++i) ss += v[i][0] * v[i][0] + v[i][1] * v[i][1] + v[i][2] * v[i][2] + v[i][3] * v[i][3];
;     ss = wave_sum(ss);
;     const float rstd = rsqrtf(ss * (1.f / DM) + 1e-6f);
; #pragma unroll
;     for (int i = 0; i < 8; ++i) {
;       const int c = (i * 64 + lane) * 4;
;       f32x4 gg = *reinterpret_cast<const f32x4*>(g + c);
;       f32x4 y = {v[i][0] * rstd * gg[0], v[i][1] * rstd * gg[1], v[i][2] * rstd * gg[2], v[i][3] * rstd * gg[3]};
;       if (MODE == 2) *reinterpret_cast<f32x4*>(p->X + (long)row * DM + c) = y;
;       else { u32x2 w = {cvtpk(y[0], y[1]), cvtpk(y[2], y[3])}; *reinterpret_cast<u32x2*>(P_H + ablk(row, c, DM / 64)) = w; }
;     }
	v_mul_f32_e32 v61, v23, v23
	v_fmac_f32_e32 v59, v26, v26
	v_fmac_f32_e32 v34, v86, v86
	v_fmac_f32_e32 v57, v32, v32
	v_pk_mul_f32 v[90:91], v[90:91], v[90:91]
	v_fmac_f32_e32 v61, v22, v22
	v_fmac_f32_e32 v59, v28, v28
	v_fmac_f32_e32 v34, v87, v87
	v_fmac_f32_e32 v57, v33, v33
	v_mov_b32_e32 v94, v11
	v_mov_b32_e32 v95, v7
	v_mov_b32_e32 v96, v20
	v_mov_b32_e32 v97, v16
	v_pk_fma_f32 v[88:89], v[88:89], v[88:89], v[90:91]
	v_fmac_f32_e32 v61, v24, v24
	v_fmac_f32_e32 v59, v29, v29
	v_add_f32_e32 v34, v34, v57
	v_mov_b32_e32 v92, v10
	v_mov_b32_e32 v93, v6
	v_mov_b32_e32 v100, v21
	v_mov_b32_e32 v101, v17
	v_pk_mul_f32 v[94:95], v[94:95], v[94:95]
	v_pk_fma_f32 v[88:89], v[96:97], v[96:97], v[88:89]
	v_fmac_f32_e32 v61, v25, v25
	v_add_f32_e32 v34, v34, v59
	v_mov_b32_e32 v98, v12
	v_mov_b32_e32 v99, v8
	v_pk_fma_f32 v[90:91], v[92:93], v[92:93], v[94:95]
	v_pk_fma_f32 v[88:89], v[100:101], v[100:101], v[88:89]
	v_add_f32_e32 v34, v34, v61
	v_mov_b32_e32 v102, v13
	v_mov_b32_e32 v103, v9
	v_pk_fma_f32 v[90:91], v[98:99], v[98:99], v[90:91]
	v_add_f32_e32 v34, v34, v88
	v_pk_fma_f32 v[90:91], v[102:103], v[102:103], v[90:91]
	v_add_f32_e32 v34, v34, v89
	v_add_f32_e32 v34, v34, v90
	v_add_f32_e32 v34, v34, v91
	ds_bpermute_b32 v57, v75, v34
	v_ashrrev_i32_e32 v90, 8, v74
	v_ashrrev_i32_e32 v91, 31, v90
	v_lshlrev_b64 v[90:91], 20, v[90:91]
	v_add_u32_e32 v74, s0, v74
	s_waitcnt lgkmcnt(0)
	v_add_f32_e32 v34, v34, v57
	ds_bpermute_b32 v57, v76, v34
	s_waitcnt lgkmcnt(0)
	v_add_f32_e32 v34, v34, v57
	ds_bpermute_b32 v57, v77, v34
	s_waitcnt lgkmcnt(0)
	v_add_f32_e32 v34, v34, v57
	ds_bpermute_b32 v57, v78, v34
	s_waitcnt lgkmcnt(0)
	v_add_f32_e32 v34, v34, v57
	ds_bpermute_b32 v57, v79, v34
	s_waitcnt lgkmcnt(0)
	v_add_f32_e32 v34, v34, v57
	ds_bpermute_b32 v57, v80, v34
	s_waitcnt lgkmcnt(0)
	v_add_f32_e32 v34, v34, v57
	v_fmamk_f32 v34, v34, 0x3a000000, v82
	v_mul_f32_e32 v57, 0x4b800000, v34
	v_cmp_gt_f32_e32 vcc, s3, v34
	s_nop 1
	v_cndmask_b32_e32 v34, v34, v57, vcc
	v_rsq_f32_e32 v34, v34
	s_nop 0
	v_mul_f32_e32 v57, 0x45800000, v34
	v_cndmask_b32_e32 v83, v34, v57, vcc
	v_mul_f32_e32 v34, v84, v83
	v_mul_f32_e32 v57, v85, v83
	v_mul_f32_e32 v59, v86, v83
	v_mul_f32_e32 v61, v87, v83
	v_mul_f32_e32 v34, v2, v34
	v_mul_f32_e32 v57, v3, v57
	v_mul_f32_e32 v59, v4, v59
	v_mul_f32_e32 v61, v5, v61
	v_cvt_pk_bf16_f32 v88, v34, v57
	v_cvt_pk_bf16_f32 v89, v59, v61
	s_load_dwordx2 s[16:17], s[14:15], 0xa8
	v_mul_f32_e32 v61, v30, v83
	v_mul_f32_e32 v63, v31, v83
	v_and_b32_e32 v34, 0x3fc0, v81
	v_mov_b32_e32 v57, v35
	s_waitcnt lgkmcnt(0)
	v_lshl_add_u64 v[30:31], s[16:17], 0, v[90:91]
	v_lshl_add_u64 v[90:91], v[30:31], 0, s[8:9]
	v_lshlrev_b32_e32 v34, 1, v34
	v_lshl_add_u64 v[30:31], v[90:91], 0, v[56:57]
	v_mov_b32_e32 v59, v35
	v_lshl_add_u64 v[30:31], v[30:31], 0, v[34:35]
	v_mul_f32_e32 v32, v32, v83
	v_mul_f32_e32 v33, v33, v83
	v_lshl_add_u64 v[30:31], v[30:31], 0, v[58:59]
	global_store_dwordx2 v[30:31], v[88:89], off
	v_mul_f32_e32 v57, v26, v83
	v_mul_f32_e32 v28, v28, v83
	v_mul_f32_e32 v29, v29, v83
	v_mul_f32_e32 v24, v24, v83
	v_mul_f32_e32 v25, v25, v83
	v_mul_f32_e32 v20, v20, v83
	v_mul_f32_e32 v21, v21, v83
	v_mul_f32_e32 v16, v16, v83
	v_mul_f32_e32 v17, v17, v83
	v_mul_f32_e32 v12, v12, v83
	v_mul_f32_e32 v13, v13, v83
	v_cmp_lt_i32_e32 vcc, s10, v74
	v_add_u32_e32 v81, s38, v81
	s_or_b64 s[6:7], vcc, s[6:7]
	v_mul_f32_e32 v30, v144, v61
	v_mul_f32_e32 v31, v145, v63
	v_mul_f32_e32 v32, v146, v32
	v_mul_f32_e32 v33, v147, v33
	v_cvt_pk_bf16_f32 v84, v30, v31
	v_cvt_pk_bf16_f32 v85, v32, v33
	v_mov_b32_e32 v61, v35
	v_mul_f32_e32 v63, v27, v83
	v_lshl_add_u64 v[26:27], v[90:91], 0, v[60:61]
	v_lshl_add_u64 v[26:27], v[26:27], 0, v[34:35]
	v_lshl_add_u64 v[26:27], v[26:27], 0, v[58:59]
	global_store_dwordx2 v[26:27], v[84:85], off
	v_mul_f32_e32 v26, v148, v57
	v_mul_f32_e32 v27, v149, v63
	v_mul_f32_e32 v28, v150, v28
	v_mul_f32_e32 v29, v151, v29
	v_cvt_pk_bf16_f32 v30, v26, v27
	v_cvt_pk_bf16_f32 v31, v28, v29
	v_mov_b32_e32 v63, v35
	v_mul_f32_e32 v32, v22, v83
	v_mul_f32_e32 v33, v23, v83
	v_lshl_add_u64 v[22:23], v[90:91], 0, v[62:63]
	v_lshl_add_u64 v[22:23], v[22:23], 0, v[34:35]
	v_lshl_add_u64 v[22:23], v[22:23], 0, v[58:59]
	global_store_dwordx2 v[22:23], v[30:31], off
	v_mul_f32_e32 v22, v32, v152
	v_mul_f32_e32 v23, v33, v153
	v_mul_f32_e32 v24, v24, v154
	v_mul_f32_e32 v25, v25, v155
	v_cvt_pk_bf16_f32 v26, v22, v23
	v_cvt_pk_bf16_f32 v27, v24, v25
	v_mul_f32_e32 v28, v18, v83
	v_mul_f32_e32 v29, v19, v83
	v_lshl_add_u64 v[18:19], v[90:91], 0, v[64:65]
	v_lshl_add_u64 v[18:19], v[18:19], 0, v[34:35]
	v_lshl_add_u64 v[18:19], v[18:19], 0, v[58:59]
	global_store_dwordx2 v[18:19], v[26:27], off
	v_mul_f32_e32 v18, v28, v156
	v_mul_f32_e32 v19, v29, v157
	v_mul_f32_e32 v20, v20, v158
	v_mul_f32_e32 v21, v21, v159
	v_cvt_pk_bf16_f32 v22, v18, v19
	v_cvt_pk_bf16_f32 v23, v20, v21
	v_mul_f32_e32 v24, v14, v83
	v_mul_f32_e32 v25, v15, v83
	v_lshl_add_u64 v[14:15], v[90:91], 0, v[66:67]
	v_lshl_add_u64 v[14:15], v[14:15], 0, v[34:35]
	v_lshl_add_u64 v[14:15], v[14:15], 0, v[58:59]
	global_store_dwordx2 v[14:15], v[22:23], off
	v_mul_f32_e32 v14, v24, v160
	v_mul_f32_e32 v15, v25, v161
	v_mul_f32_e32 v16, v16, v162
	v_mul_f32_e32 v17, v17, v163
	v_cvt_pk_bf16_f32 v18, v14, v15
	v_cvt_pk_bf16_f32 v19, v16, v17
	v_mul_f32_e32 v20, v10, v83
	v_mul_f32_e32 v21, v11, v83
	v_lshl_add_u64 v[10:11], v[90:91], 0, v[68:69]
	v_lshl_add_u64 v[10:11], v[10:11], 0, v[34:35]
	v_lshl_add_u64 v[10:11], v[10:11], 0, v[58:59]
	global_store_dwordx2 v[10:11], v[18:19], off
	v_mul_f32_e32 v18, v8, v83
	v_mul_f32_e32 v19, v9, v83
	v_lshl_add_u64 v[8:9], v[90:91], 0, v[72:73]
	v_lshl_add_u64 v[8:9], v[8:9], 0, v[34:35]
	v_lshl_add_u64 v[8:9], v[8:9], 0, v[58:59]
	v_mul_f32_e32 v10, v20, v164
	v_mul_f32_e32 v11, v21, v165
	v_mul_f32_e32 v12, v12, v166
	v_mul_f32_e32 v13, v13, v167
	v_cvt_pk_bf16_f32 v14, v10, v11
	v_cvt_pk_bf16_f32 v15, v12, v13
	v_mul_f32_e32 v16, v6, v83
	v_mul_f32_e32 v17, v7, v83
	v_lshl_add_u64 v[6:7], v[90:91], 0, v[70:71]
	v_lshl_add_u64 v[6:7], v[6:7], 0, v[34:35]
	v_lshl_add_u64 v[6:7], v[6:7], 0, v[58:59]
	global_store_dwordx2 v[6:7], v[14:15], off
	v_mul_f32_e32 v6, v16, v168
	v_mul_f32_e32 v7, v17, v169
	v_mul_f32_e32 v10, v18, v170
	v_mul_f32_e32 v11, v19, v171
	v_cvt_pk_bf16_f32 v6, v6, v7
	v_cvt_pk_bf16_f32 v7, v10, v11
	global_store_dwordx2 v[8:9], v[6:7], off
	s_andn2_b64 exec, exec, s[6:7]
	s_cbranch_execnz .LBB0_69

; __device__ __forceinline__ int mytid(int wv) { return (wv << 6) | (int)__builtin_amdgcn_mbcnt_hi(~0u, __builtin_amdgcn_mbcnt_lo(~0u, 0u)); }
; #define p getp()
; template <int MODE>
; __device__ __forceinline__ void rms_rows(KP p, const float* __restrict__ g, int wv) {
;   int tid = mytid(wv); asm volatile("" : "+v"(tid));
;   const int wid = tid >> 6, lane = tid & 63;
;   for (int row = blockIdx.x * 8 + wid; row < TOK; row += gridDim.x * 8) {
;     const float* src;
;     if (MODE == 0) src = (row < SEQ) ? p->x_prompt + (long)row * DM : p->x_sample + (long)(row - SEQ) * DM;
;     else src = p->X + (long)row * DM;
;     f32x4 v[8];
; #pragma unroll
;     for (int i = 0; i < 8; ++i) v[i] = *reinterpret_cast<const f32x4*>(src + (i * 64 + lane) * 4);
;     float ss = 0.f;
; #pragma unroll
;     for (int i = 0; i < 8; ++i) ss += v[i][0] * v[i][0] + v[i][1] * v[i][1] + v[i][2] * v[i][2] + v[i][3] * v[i][3];
;     ss = wave_sum(ss);
;     const float rstd = rsqrtf(ss * (1.f / DM) + 1e-6f);
.LBB0_539:
	s_or_b64 exec, exec, s[4:5]
	s_mov_b64 s[4:5], s[90:91]
	s_mov_b64 s[14:15], s[90:91]
	v_mov_b32_e32 v0, v192
	s_barrier
	v_readlane_b32 s0, v255, 8
	v_ashrrev_i32_e32 v4, 6, v0
	s_nop 0
	v_add_u32_e32 v20, s0, v4
	s_mov_b32 s0, 0xc000
	v_cmp_gt_i32_e32 vcc, s0, v20
	s_and_saveexec_b64 s[8:9], vcc
	s_cbranch_execz .LBB0_542
	s_load_dwordx2 s[12:13], s[14:15], 0x18
	s_load_dwordx2 s[10:11], s[4:5], 0xa0
	v_lshlrev_b32_e32 v5, 2, v0
	v_and_b32_e32 v6, 0xfc, v5
	v_and_b32_e32 v0, 64, v200
	v_lshlrev_b32_e32 v22, 2, v6
	v_add_u32_e32 v7, 64, v0
	s_waitcnt lgkmcnt(0)
	global_load_dwordx4 v[0:3], v22, s[12:13]
	v_cmp_lt_i32_e32 vcc, v206, v7
	s_mov_b32 s0, 0x1c000
	v_or_b32_e32 v10, 0x400, v6
	v_cndmask_b32_e32 v8, v200, v206, vcc
	v_lshlrev_b32_e32 v60, 2, v8
	v_xor_b32_e32 v8, 16, v200
	v_cmp_lt_i32_e32 vcc, v8, v7
	v_mov_b32_e32 v23, 0
	v_or_b32_e32 v12, 0x500, v6
	v_cndmask_b32_e32 v8, v200, v8, vcc
	v_lshlrev_b32_e32 v61, 2, v8
	v_xor_b32_e32 v8, 8, v200
	v_cmp_lt_i32_e32 vcc, v8, v7
	v_lshl_add_u64 v[24:25], s[12:13], 0, v[22:23]
	v_or_b32_e32 v14, 0x600, v6
	v_cndmask_b32_e32 v8, v200, v8, vcc
	v_lshlrev_b32_e32 v62, 2, v8
	v_xor_b32_e32 v8, 4, v200
	v_cmp_lt_i32_e32 vcc, v8, v7
	v_lshlrev_b32_e32 v22, 2, v10
	v_or_b32_e32 v16, 0x700, v6
	v_cndmask_b32_e32 v8, v200, v8, vcc
	v_cmp_lt_i32_e32 vcc, v201, v7
	v_lshlrev_b32_e32 v63, 2, v8
	v_lshl_add_u64 v[26:27], s[12:13], 0, v[22:23]
	v_cndmask_b32_e32 v8, v200, v201, vcc
	v_lshlrev_b32_e32 v64, 2, v8
	v_xor_b32_e32 v8, 1, v200
	v_cmp_lt_i32_e32 vcc, v8, v7
	v_lshlrev_b32_e32 v22, 2, v12
	v_lshl_add_u64 v[28:29], s[12:13], 0, v[22:23]
	v_cndmask_b32_e32 v7, v200, v8, vcc
	v_lshlrev_b32_e32 v65, 2, v7
	v_and_b32_e32 v8, 60, v5
	v_lshlrev_b32_e32 v5, 8, v6
	v_mov_b32_e32 v7, 0x10000
	v_bitop3_b32 v46, v5, s0, v7 bitop3:0xc8
	s_mov_b32 s0, 0x2c000
	v_mov_b32_e32 v7, 0x20000
	v_bitop3_b32 v48, v5, s0, v7 bitop3:0xc8
	s_mov_b32 s0, 0x3c000
	v_mov_b32_e32 v7, 0x30000
	v_and_b32_e32 v18, 0xc000, v5
	v_bitop3_b32 v50, v5, s0, v7 bitop3:0xc8
	v_lshlrev_b32_e32 v5, 8, v10
	v_and_b32_e32 v52, 0x4c000, v5
	v_lshlrev_b32_e32 v5, 8, v12
	v_and_b32_e32 v54, 0x5c000, v5
	v_lshlrev_b32_e32 v5, 8, v14
	v_lshlrev_b32_e32 v22, 2, v14
	v_and_b32_e32 v56, 0x6c000, v5
	v_lshlrev_b32_e32 v5, 8, v16
	v_lshl_add_u64 v[30:31], s[12:13], 0, v[22:23]
	v_lshlrev_b32_e32 v22, 2, v16
	v_and_b32_e32 v58, 0x7c000, v5
	v_readlane_b32 s1, v255, 7
	v_lshl_add_u64 v[32:33], s[12:13], 0, v[22:23]
	s_lshl_b32 s0, s88, 3
	v_lshl_add_u32 v66, v4, 6, s1
	s_mov_b64 s[12:13], 0
	v_lshlrev_b32_e32 v34, 2, v6
	v_lshlrev_b32_e32 v36, 2, v10
	v_lshlrev_b32_e32 v38, 2, v12
	v_lshlrev_b32_e32 v40, 2, v14
	v_lshlrev_b32_e32 v42, 2, v16
	v_mov_b32_e32 v67, 0x358637bd
	s_mov_b32 s1, 0x800000
	s_mov_b64 s[14:15], 0xba40000
	v_lshlrev_b32_e32 v22, 1, v18
	v_lshlrev_b32_e32 v44, 1, v8
	v_lshlrev_b32_e32 v46, 1, v46
	v_lshlrev_b32_e32 v48, 1, v48
	v_lshlrev_b32_e32 v50, 1, v50
	v_lshlrev_b32_e32 v52, 1, v52
	v_lshlrev_b32_e32 v54, 1, v54
	v_lshlrev_b32_e32 v56, 1, v56
	v_lshlrev_b32_e32 v58, 1, v58
	s_mov_b32 s3, 0xbfff
	v_mov_b32_e32 v35, v23
	v_mov_b32_e32 v37, v23
	v_mov_b32_e32 v39, v23
	v_mov_b32_e32 v41, v23
	v_mov_b32_e32 v43, v23
	global_load_dwordx4 v[144:147], v[24:25], off offset:1024
	global_load_dwordx4 v[148:151], v[24:25], off offset:2048
	global_load_dwordx4 v[152:155], v[24:25], off offset:3072
	global_load_dwordx4 v[156:159], v[26:27], off
	global_load_dwordx4 v[160:163], v[28:29], off
	global_load_dwordx4 v[164:167], v[30:31], off
	global_load_dwordx4 v[168:171], v[32:33], off
.LBB0_541:
	v_ashrrev_i32_e32 v21, 31, v20
	v_lshlrev_b64 v[4:5], 13, v[20:21]
	v_lshl_add_u64 v[4:5], s[10:11], 0, v[4:5]
	v_lshl_add_u64 v[84:85], v[4:5], 0, v[34:35]
	v_lshl_add_u64 v[86:87], v[4:5], 0, v[36:37]
	v_lshl_add_u64 v[88:89], v[4:5], 0, v[38:39]
	v_lshl_add_u64 v[90:91], v[4:5], 0, v[40:41]
	v_lshl_add_u64 v[92:93], v[4:5], 0, v[42:43]
	global_load_dwordx4 v[68:71], v[84:85], off
	global_load_dwordx4 v[72:75], v[84:85], off offset:1024
	global_load_dwordx4 v[76:79], v[84:85], off offset:2048
	global_load_dwordx4 v[80:83], v[84:85], off offset:3072
	global_load_dwordx4 v[16:19], v[86:87], off
	global_load_dwordx4 v[12:15], v[88:89], off
	global_load_dwordx4 v[8:11], v[90:91], off
	global_load_dwordx4 v[4:7], v[92:93], off
	v_mov_b32_e32 v57, v23
	v_mov_b32_e32 v59, v23
	s_waitcnt vmcnt(7)
	v_mul_f32_e32 v21, v69, v69
	s_waitcnt vmcnt(6)
	v_mul_f32_e32 v45, v73, v73
	s_waitcnt vmcnt(5)
	v_mul_f32_e32 v47, v77, v77
	v_fmac_f32_e32 v21, v68, v68
	v_fmac_f32_e32 v45, v72, v72
	s_waitcnt vmcnt(4)
	v_mul_f32_e32 v49, v81, v81
	s_waitcnt vmcnt(3)
	v_mov_b32_e32 v86, v17
	s_waitcnt vmcnt(2)
	v_mov_b32_e32 v87, v13
	v_fmac_f32_e32 v47, v76, v76
	v_fmac_f32_e32 v21, v70, v70
	v_fmac_f32_e32 v45, v74, v74
	v_mov_b32_e32 v84, v16
	v_mov_b32_e32 v85, v12
	v_fmac_f32_e32 v49, v80, v80
	v_pk_mul_f32 v[86:87], v[86:87], v[86:87]
	v_fmac_f32_e32 v47, v78, v78
	v_fmac_f32_e32 v21, v71, v71
	v_fmac_f32_e32 v45, v75, v75
	v_mov_b32_e32 v88, v18
	v_mov_b32_e32 v89, v14
	s_waitcnt vmcnt(1)
	v_mov_b32_e32 v94, v9
	s_waitcnt vmcnt(0)
	v_mov_b32_e32 v95, v5
	v_fmac_f32_e32 v49, v82, v82
	v_pk_fma_f32 v[84:85], v[84:85], v[84:85], v[86:87]
	v_fmac_f32_e32 v47, v79, v79
	v_add_f32_e32 v21, v21, v45
	v_mov_b32_e32 v90, v19
	v_mov_b32_e32 v91, v15
	v_mov_b32_e32 v92, v8
	v_mov_b32_e32 v93, v4
	v_pk_mul_f32 v[94:95], v[94:95], v[94:95]
	v_fmac_f32_e32 v49, v83, v83
	v_pk_fma_f32 v[84:85], v[88:89], v[88:89], v[84:85]
	v_add_f32_e32 v21, v21, v47
	v_mov_b32_e32 v96, v10
	v_mov_b32_e32 v97, v6
	v_pk_fma_f32 v[86:87], v[92:93], v[92:93], v[94:95]
	v_pk_fma_f32 v[84:85], v[90:91], v[90:91], v[84:85]
	v_add_f32_e32 v21, v21, v49
	v_mov_b32_e32 v98, v11
	v_mov_b32_e32 v99, v7
	v_pk_fma_f32 v[86:87], v[96:97], v[96:97], v[86:87]
	v_add_f32_e32 v21, v21, v84
	v_pk_fma_f32 v[86:87], v[98:99], v[98:99], v[86:87]
	v_add_f32_e32 v21, v21, v85
	v_add_f32_e32 v21, v21, v86
	v_add_f32_e32 v21, v21, v87
	ds_bpermute_b32 v45, v60, v21
	v_ashrrev_i32_e32 v86, 8, v20
	v_ashrrev_i32_e32 v87, 31, v86
	v_lshlrev_b64 v[86:87], 20, v[86:87]
	v_mov_b32_e32 v89, v23
	s_waitcnt lgkmcnt(0)
; __device__ __forceinline__ long ablk(int row, int col, int nkt) { return ((long)(row >> 8) * nkt + (col >> 6)) * 16384 + (row & 255) * 64 + (col & 63); }
; #define p getp()
; template <int MODE>
; __device__ __forceinline__ void rms_rows(KP p, const float* __restrict__ g, int wv) {
;     ...
;     const float rstd = rsqrtf(ss * (1.f / DM) + 1e-6f);
; #pragma unroll
;     for (int i = 0; i < 8; ++i) {
;       const int c = (i * 64 + lane) * 4;
;       f32x4 gg = *reinterpret_cast<const f32x4*>(g + c);
;       f32x4 y = {v[i][0] * rstd * gg[0], v[i][1] * rstd * gg[1], v[i][2] * rstd * gg[2], v[i][3] * rstd * gg[3]};
;       if (MODE == 2) *reinterpret_cast<f32x4*>(p->X + (long)row * DM + c) = y;
;       else { u32x2 w = {cvtpk(y[0], y[1]), cvtpk(y[2], y[3])}; *reinterpret_cast<u32x2*>(P_H + ablk(row, c, DM / 64)) = w; }
;     }
	v_add_f32_e32 v21, v21, v45
	ds_bpermute_b32 v45, v61, v21
	v_add_u32_e32 v20, s0, v20
	s_waitcnt lgkmcnt(0)
	v_add_f32_e32 v21, v21, v45
	ds_bpermute_b32 v45, v62, v21
	s_waitcnt lgkmcnt(0)
	v_add_f32_e32 v21, v21, v45
	ds_bpermute_b32 v45, v63, v21
	s_waitcnt lgkmcnt(0)
	v_add_f32_e32 v21, v21, v45
	ds_bpermute_b32 v45, v64, v21
	s_waitcnt lgkmcnt(0)
	v_add_f32_e32 v21, v21, v45
	ds_bpermute_b32 v45, v65, v21
	s_waitcnt lgkmcnt(0)
	v_add_f32_e32 v21, v21, v45
	v_fmamk_f32 v21, v21, 0x3a000000, v67
	v_mul_f32_e32 v45, 0x4b800000, v21
	v_cmp_gt_f32_e32 vcc, s1, v21
	s_nop 1
	v_cndmask_b32_e32 v21, v21, v45, vcc
	v_rsq_f32_e32 v21, v21
	s_nop 0
	v_mul_f32_e32 v45, 0x45800000, v21
	v_cndmask_b32_e32 v21, v21, v45, vcc
	v_mul_f32_e32 v45, v68, v21
	v_mul_f32_e32 v47, v69, v21
	v_mul_f32_e32 v49, v70, v21
	v_mul_f32_e32 v51, v71, v21
	v_mul_f32_e32 v45, v0, v45
	v_mul_f32_e32 v47, v1, v47
	v_mul_f32_e32 v49, v2, v49
	v_mul_f32_e32 v51, v3, v51
	v_cvt_pk_bf16_f32 v84, v45, v47
	v_cvt_pk_bf16_f32 v85, v49, v51
	s_load_dwordx2 s[16:17], s[4:5], 0xa8
	v_and_b32_e32 v47, 0x3fc0, v66
	v_lshlrev_b32_e32 v88, 1, v47
	v_mul_f32_e32 v47, v72, v21
	v_mul_f32_e32 v49, v73, v21
	s_waitcnt lgkmcnt(0)
	v_lshl_add_u64 v[72:73], s[16:17], 0, v[86:87]
	v_lshl_add_u64 v[72:73], v[72:73], 0, s[14:15]
	v_mul_f32_e32 v51, v74, v21
	v_mul_f32_e32 v53, v75, v21
	v_lshl_add_u64 v[74:75], v[72:73], 0, v[22:23]
	v_mov_b32_e32 v45, v23
	v_lshl_add_u64 v[74:75], v[74:75], 0, v[88:89]
	v_lshl_add_u64 v[74:75], v[74:75], 0, v[44:45]
	global_store_dwordx2 v[74:75], v[84:85], off
	v_mul_f32_e32 v55, v79, v21
	v_mul_f32_e32 v18, v18, v21
	v_mul_f32_e32 v19, v19, v21
	v_mul_f32_e32 v14, v14, v21
	v_mul_f32_e32 v15, v15, v21
	v_mul_f32_e32 v10, v10, v21
	v_mul_f32_e32 v11, v11, v21
	v_cmp_lt_i32_e32 vcc, s3, v20
	v_add_u32_e32 v66, s38, v66
	s_or_b64 s[12:13], vcc, s[12:13]
	v_mul_f32_e32 v47, v144, v47
	v_mul_f32_e32 v49, v145, v49
	v_mul_f32_e32 v51, v146, v51
	v_mul_f32_e32 v53, v147, v53
	v_cvt_pk_bf16_f32 v74, v47, v49
	v_cvt_pk_bf16_f32 v75, v51, v53
	v_mov_b32_e32 v47, v23
	v_mul_f32_e32 v49, v76, v21
	v_mul_f32_e32 v51, v77, v21
	v_lshl_add_u64 v[76:77], v[72:73], 0, v[46:47]
	v_lshl_add_u64 v[76:77], v[76:77], 0, v[88:89]
	v_mul_f32_e32 v53, v78, v21
	v_lshl_add_u64 v[76:77], v[76:77], 0, v[44:45]
	global_store_dwordx2 v[76:77], v[74:75], off
	v_mul_f32_e32 v47, v148, v49
	v_mul_f32_e32 v49, v149, v51
	v_mul_f32_e32 v51, v150, v53
	v_mul_f32_e32 v53, v151, v55
	v_cvt_pk_bf16_f32 v74, v47, v49
	v_cvt_pk_bf16_f32 v75, v51, v53
	v_mov_b32_e32 v49, v23
	v_lshl_add_u64 v[76:77], v[72:73], 0, v[48:49]
	v_lshl_add_u64 v[76:77], v[76:77], 0, v[88:89]
	v_mul_f32_e32 v47, v80, v21
	v_mul_f32_e32 v51, v81, v21
	v_mul_f32_e32 v53, v82, v21
	v_mul_f32_e32 v55, v83, v21
	v_lshl_add_u64 v[76:77], v[76:77], 0, v[44:45]
	global_store_dwordx2 v[76:77], v[74:75], off
	v_mul_f32_e32 v47, v47, v152
	v_mul_f32_e32 v49, v51, v153
	v_mul_f32_e32 v51, v53, v154
	v_mul_f32_e32 v53, v55, v155
	v_cvt_pk_bf16_f32 v74, v47, v49
	v_cvt_pk_bf16_f32 v75, v51, v53
	v_mov_b32_e32 v51, v23
	v_mul_f32_e32 v47, v16, v21
	v_mul_f32_e32 v49, v17, v21
	v_lshl_add_u64 v[16:17], v[72:73], 0, v[50:51]
	v_lshl_add_u64 v[16:17], v[16:17], 0, v[88:89]
	v_lshl_add_u64 v[16:17], v[16:17], 0, v[44:45]
	global_store_dwordx2 v[16:17], v[74:75], off
	v_mov_b32_e32 v53, v23
	v_mov_b32_e32 v55, v23
	v_mul_f32_e32 v16, v47, v156
	v_mul_f32_e32 v17, v49, v157
	v_mul_f32_e32 v18, v18, v158
	v_mul_f32_e32 v19, v19, v159
	v_cvt_pk_bf16_f32 v68, v16, v17
	v_cvt_pk_bf16_f32 v69, v18, v19
	v_mul_f32_e32 v47, v12, v21
	v_mul_f32_e32 v49, v13, v21
	v_lshl_add_u64 v[12:13], v[72:73], 0, v[52:53]
	v_lshl_add_u64 v[12:13], v[12:13], 0, v[88:89]
	v_lshl_add_u64 v[12:13], v[12:13], 0, v[44:45]
	global_store_dwordx2 v[12:13], v[68:69], off
	v_mul_f32_e32 v12, v47, v160
	v_mul_f32_e32 v13, v49, v161
	v_mul_f32_e32 v14, v14, v162
	v_mul_f32_e32 v15, v15, v163
	v_cvt_pk_bf16_f32 v16, v12, v13
	v_cvt_pk_bf16_f32 v17, v14, v15
	v_mul_f32_e32 v18, v8, v21
	v_mul_f32_e32 v19, v9, v21
	v_lshl_add_u64 v[8:9], v[72:73], 0, v[54:55]
	v_lshl_add_u64 v[8:9], v[8:9], 0, v[88:89]
	v_lshl_add_u64 v[8:9], v[8:9], 0, v[44:45]
	global_store_dwordx2 v[8:9], v[16:17], off
	v_mul_f32_e32 v16, v6, v21
	v_mul_f32_e32 v17, v7, v21
	v_lshl_add_u64 v[6:7], v[72:73], 0, v[58:59]
	v_lshl_add_u64 v[6:7], v[6:7], 0, v[88:89]
	v_lshl_add_u64 v[6:7], v[6:7], 0, v[44:45]
	v_mul_f32_e32 v8, v18, v164
	v_mul_f32_e32 v9, v19, v165
	v_mul_f32_e32 v10, v10, v166
	v_mul_f32_e32 v11, v11, v167
	v_cvt_pk_bf16_f32 v12, v8, v9
	v_cvt_pk_bf16_f32 v13, v10, v11
	v_mul_f32_e32 v14, v4, v21
	v_mul_f32_e32 v15, v5, v21
	v_lshl_add_u64 v[4:5], v[72:73], 0, v[56:57]
	v_lshl_add_u64 v[4:5], v[4:5], 0, v[88:89]
	v_lshl_add_u64 v[4:5], v[4:5], 0, v[44:45]
	global_store_dwordx2 v[4:5], v[12:13], off
	v_mul_f32_e32 v4, v14, v168
	v_mul_f32_e32 v5, v15, v169
	v_mul_f32_e32 v8, v16, v170
	v_mul_f32_e32 v9, v17, v171
	v_cvt_pk_bf16_f32 v4, v4, v5
	v_cvt_pk_bf16_f32 v5, v8, v9
	global_store_dwordx2 v[6:7], v[4:5], off
	s_andn2_b64 exec, exec, s[12:13]
	s_cbranch_execnz .LBB0_541

; __device__ __forceinline__ int mytid(int wv) { return (wv << 6) | (int)__builtin_amdgcn_mbcnt_hi(~0u, __builtin_amdgcn_mbcnt_lo(~0u, 0u)); }
; #define p getp()
; template <int MODE>
; __device__ __forceinline__ void rms_rows(KP p, const float* __restrict__ g, int wv) {
;   int tid = mytid(wv); asm volatile("" : "+v"(tid));
;   const int wid = tid >> 6, lane = tid & 63;
;   for (int row = blockIdx.x * 8 + wid; row < TOK; row += gridDim.x * 8) {
;     const float* src;
;     if (MODE == 0) src = (row < SEQ) ? p->x_prompt + (long)row * DM : p->x_sample + (long)(row - SEQ) * DM;
;     else src = p->X + (long)row * DM;
;     f32x4 v[8];
; #pragma unroll
;     for (int i = 0; i < 8; ++i) v[i] = *reinterpret_cast<const f32x4*>(src + (i * 64 + lane) * 4);
;     float ss = 0.f;
; #pragma unroll
;     for (int i = 0; i < 8; ++i) ss += v[i][0] * v[i][0] + v[i][1] * v[i][1] + v[i][2] * v[i][2] + v[i][3] * v[i][3];
;     ss = wave_sum(ss);
;     const float rstd = rsqrtf(ss * (1.f / DM) + 1e-6f);
.LBB0_673:
	s_or_b64 exec, exec, s[6:7]
	s_mov_b64 s[6:7], s[90:91]
	s_mov_b64 s[12:13], s[90:91]
	v_mov_b32_e32 v5, v192
	s_barrier
	v_readlane_b32 s0, v255, 8
	v_ashrrev_i32_e32 v4, 6, v5
	s_nop 0
	v_add_u32_e32 v20, s0, v4
	s_mov_b32 s0, 0xc000
	v_cmp_gt_i32_e32 vcc, s0, v20
	s_and_saveexec_b64 s[8:9], vcc
	s_cbranch_execz .LBB0_676
	s_load_dwordx2 s[0:1], s[12:13], 0x10
	s_load_dwordx2 s[10:11], s[6:7], 0xa0
	v_lshlrev_b32_e32 v7, 2, v5
	v_and_b32_e32 v0, 64, v200
	v_and_b32_e32 v6, 0xfc, v7
	s_waitcnt lgkmcnt(0)
	s_add_u32 s12, s0, 0x2000
	v_add_u32_e32 v8, 64, v0
	s_addc_u32 s13, s1, 0
	v_lshlrev_b32_e32 v0, 2, v6
	global_load_dwordx4 v[0:3], v0, s[12:13]
	v_cmp_lt_i32_e32 vcc, v206, v8
	v_lshlrev_b32_e32 v5, 10, v5
	v_and_b32_e32 v18, 0xc000, v5
	v_cndmask_b32_e32 v9, v200, v206, vcc
	v_lshlrev_b32_e32 v64, 2, v9
	v_xor_b32_e32 v9, 16, v200
	v_cmp_lt_i32_e32 vcc, v9, v8
	v_mov_b32_e32 v23, 0
	v_or_b32_e32 v11, 0x300, v6
	v_cndmask_b32_e32 v9, v200, v9, vcc
	v_lshlrev_b32_e32 v65, 2, v9
	v_xor_b32_e32 v9, 8, v200
	v_cmp_lt_i32_e32 vcc, v9, v8
	v_or_b32_e32 v10, 0x400, v6
	v_or_b32_e32 v12, 0x500, v6
	v_cndmask_b32_e32 v9, v200, v9, vcc
	v_lshlrev_b32_e32 v66, 2, v9
	v_xor_b32_e32 v9, 4, v200
	v_cmp_lt_i32_e32 vcc, v9, v8
	v_or_b32_e32 v14, 0x600, v6
	v_or_b32_e32 v16, 0x700, v6
	v_cndmask_b32_e32 v9, v200, v9, vcc
	v_cmp_lt_i32_e32 vcc, v201, v8
	v_lshlrev_b32_e32 v67, 2, v9
	v_readlane_b32 s1, v255, 7
	v_cndmask_b32_e32 v9, v200, v201, vcc
	v_lshlrev_b32_e32 v68, 2, v9
	v_xor_b32_e32 v9, 1, v200
	v_cmp_lt_i32_e32 vcc, v9, v8
	s_lshl_b32 s0, s88, 3
	v_lshl_add_u32 v70, v4, 6, s1
	v_cndmask_b32_e32 v8, v200, v9, vcc
	v_lshlrev_b32_e32 v69, 2, v8
	v_and_b32_e32 v8, 60, v7
	v_or_b32_e32 v7, 0x100, v6
	v_or_b32_e32 v9, 0x200, v6
	v_lshlrev_b32_e32 v5, 8, v7
	v_lshlrev_b32_e32 v22, 2, v7
	v_and_b32_e32 v50, 0x1c000, v5
	v_lshlrev_b32_e32 v5, 8, v9
	v_lshl_add_u64 v[24:25], s[12:13], 0, v[22:23]
	v_lshlrev_b32_e32 v22, 2, v9
	v_and_b32_e32 v52, 0x2c000, v5
	v_lshlrev_b32_e32 v5, 8, v11
	v_lshl_add_u64 v[26:27], s[12:13], 0, v[22:23]
	v_lshlrev_b32_e32 v22, 2, v11
	v_and_b32_e32 v54, 0x3c000, v5
	v_lshlrev_b32_e32 v5, 8, v10
	v_lshl_add_u64 v[28:29], s[12:13], 0, v[22:23]
	v_lshlrev_b32_e32 v22, 2, v10
	v_and_b32_e32 v56, 0x4c000, v5
	v_lshlrev_b32_e32 v5, 8, v12
	v_lshl_add_u64 v[30:31], s[12:13], 0, v[22:23]
	v_lshlrev_b32_e32 v22, 2, v12
	v_and_b32_e32 v58, 0x5c000, v5
	v_lshlrev_b32_e32 v5, 8, v14
	v_lshl_add_u64 v[32:33], s[12:13], 0, v[22:23]
	v_lshlrev_b32_e32 v22, 2, v14
	v_and_b32_e32 v60, 0x6c000, v5
	v_lshlrev_b32_e32 v5, 8, v16
	v_lshl_add_u64 v[34:35], s[12:13], 0, v[22:23]
	v_lshlrev_b32_e32 v22, 2, v16
	v_and_b32_e32 v62, 0x7c000, v5
	v_lshl_add_u64 v[36:37], s[12:13], 0, v[22:23]
	s_mov_b64 s[12:13], 0
	v_lshlrev_b32_e32 v22, 2, v6
	v_lshlrev_b32_e32 v38, 2, v10
	v_lshlrev_b32_e32 v40, 2, v12
	v_lshlrev_b32_e32 v42, 2, v14
	v_lshlrev_b32_e32 v44, 2, v16
	v_mov_b32_e32 v71, 0x358637bd
	s_mov_b32 s1, 0x800000
	s_mov_b64 s[14:15], 0xba40000
	v_lshlrev_b32_e32 v46, 1, v18
	v_lshlrev_b32_e32 v48, 1, v8
	v_lshlrev_b32_e32 v50, 1, v50
	v_lshlrev_b32_e32 v52, 1, v52
	v_lshlrev_b32_e32 v54, 1, v54
	v_lshlrev_b32_e32 v56, 1, v56
	v_lshlrev_b32_e32 v58, 1, v58
	v_lshlrev_b32_e32 v60, 1, v60
	v_lshlrev_b32_e32 v62, 1, v62
	s_mov_b32 s3, 0xbfff
	global_load_dwordx4 v[144:147], v[24:25], off
	global_load_dwordx4 v[148:151], v[26:27], off
	global_load_dwordx4 v[152:155], v[28:29], off
	global_load_dwordx4 v[156:159], v[30:31], off
	global_load_dwordx4 v[160:163], v[32:33], off
	global_load_dwordx4 v[164:167], v[34:35], off
	global_load_dwordx4 v[168:171], v[36:37], off
.LBB0_675:
	v_ashrrev_i32_e32 v21, 31, v20
	v_lshlrev_b64 v[4:5], 13, v[20:21]
	v_lshl_add_u64 v[4:5], s[10:11], 0, v[4:5]
	v_mov_b32_e32 v39, v23
	v_mov_b32_e32 v41, v23
	v_mov_b32_e32 v43, v23
	v_mov_b32_e32 v45, v23
	v_lshl_add_u64 v[88:89], v[4:5], 0, v[22:23]
	v_lshl_add_u64 v[90:91], v[4:5], 0, v[38:39]
	v_lshl_add_u64 v[92:93], v[4:5], 0, v[40:41]
	v_lshl_add_u64 v[94:95], v[4:5], 0, v[42:43]
	v_lshl_add_u64 v[96:97], v[4:5], 0, v[44:45]
	global_load_dwordx4 v[72:75], v[88:89], off
	global_load_dwordx4 v[76:79], v[88:89], off offset:1024
	global_load_dwordx4 v[80:83], v[88:89], off offset:2048
	global_load_dwordx4 v[84:87], v[88:89], off offset:3072
	global_load_dwordx4 v[16:19], v[90:91], off
	global_load_dwordx4 v[12:15], v[92:93], off
	global_load_dwordx4 v[8:11], v[94:95], off
	global_load_dwordx4 v[4:7], v[96:97], off
	v_mov_b32_e32 v47, v23
	v_mov_b32_e32 v49, v23
	v_mov_b32_e32 v51, v23
	v_mov_b32_e32 v53, v23
	v_mov_b32_e32 v55, v23
	v_mov_b32_e32 v57, v23
	v_mov_b32_e32 v59, v23
	v_mov_b32_e32 v61, v23
	v_mov_b32_e32 v63, v23
	s_waitcnt vmcnt(7)
	v_mul_f32_e32 v21, v73, v73
	s_waitcnt vmcnt(6)
	v_mul_f32_e32 v39, v77, v77
	s_waitcnt vmcnt(5)
	v_mul_f32_e32 v41, v81, v81
	v_fmac_f32_e32 v21, v72, v72
	v_fmac_f32_e32 v39, v76, v76
	s_waitcnt vmcnt(4)
	v_mul_f32_e32 v43, v85, v85
	s_waitcnt vmcnt(3)
	v_mov_b32_e32 v90, v17
	s_waitcnt vmcnt(2)
	v_mov_b32_e32 v91, v13
	v_fmac_f32_e32 v41, v80, v80
	v_fmac_f32_e32 v21, v74, v74
	v_fmac_f32_e32 v39, v78, v78
	v_mov_b32_e32 v88, v16
	v_mov_b32_e32 v89, v12
	v_fmac_f32_e32 v43, v84, v84
	v_pk_mul_f32 v[90:91], v[90:91], v[90:91]
	v_fmac_f32_e32 v41, v82, v82
	v_fmac_f32_e32 v21, v75, v75
	v_fmac_f32_e32 v39, v79, v79
	v_mov_b32_e32 v92, v18
	v_mov_b32_e32 v93, v14
	s_waitcnt vmcnt(1)
	v_mov_b32_e32 v98, v9
	s_waitcnt vmcnt(0)
; __device__ __forceinline__ long ablk(int row, int col, int nkt) { return ((long)(row >> 8) * nkt + (col >> 6)) * 16384 + (row & 255) * 64 + (col & 63); }
; #define p getp()
; template <int MODE>
; __device__ __forceinline__ void rms_rows(KP p, const float* __restrict__ g, int wv) {
;     ...
;     const float rstd = rsqrtf(ss * (1.f / DM) + 1e-6f);
; #pragma unroll
;     for (int i = 0; i < 8; ++i) {
;       const int c = (i * 64 + lane) * 4;
;       f32x4 gg = *reinterpret_cast<const f32x4*>(g + c);
;       f32x4 y = {v[i][0] * rstd * gg[0], v[i][1] * rstd * gg[1], v[i][2] * rstd * gg[2], v[i][3] * rstd * gg[3]};
;       if (MODE == 2) *reinterpret_cast<f32x4*>(p->X + (long)row * DM + c) = y;
;       else { u32x2 w = {cvtpk(y[0], y[1]), cvtpk(y[2], y[3])}; *reinterpret_cast<u32x2*>(P_H + ablk(row, c, DM / 64)) = w; }
;     }
	v_mov_b32_e32 v99, v5
	v_fmac_f32_e32 v43, v86, v86
	v_pk_fma_f32 v[88:89], v[88:89], v[88:89], v[90:91]
	v_fmac_f32_e32 v41, v83, v83
	v_add_f32_e32 v21, v21, v39
	v_mov_b32_e32 v94, v19
	v_mov_b32_e32 v95, v15
	v_mov_b32_e32 v96, v8
	v_mov_b32_e32 v97, v4
	v_pk_mul_f32 v[98:99], v[98:99], v[98:99]
	v_fmac_f32_e32 v43, v87, v87
	v_pk_fma_f32 v[88:89], v[92:93], v[92:93], v[88:89]
	v_add_f32_e32 v21, v21, v41
	v_mov_b32_e32 v100, v10
	v_mov_b32_e32 v101, v6
	v_pk_fma_f32 v[90:91], v[96:97], v[96:97], v[98:99]
	v_pk_fma_f32 v[88:89], v[94:95], v[94:95], v[88:89]
	v_add_f32_e32 v21, v21, v43
	v_mov_b32_e32 v102, v11
	v_mov_b32_e32 v103, v7
	v_pk_fma_f32 v[90:91], v[100:101], v[100:101], v[90:91]
	v_add_f32_e32 v21, v21, v88
	v_pk_fma_f32 v[90:91], v[102:103], v[102:103], v[90:91]
	v_add_f32_e32 v21, v21, v89
	v_add_f32_e32 v21, v21, v90
	v_add_f32_e32 v21, v21, v91
	ds_bpermute_b32 v39, v64, v21
	v_ashrrev_i32_e32 v90, 8, v20
	v_ashrrev_i32_e32 v91, 31, v90
	v_lshlrev_b64 v[90:91], 20, v[90:91]
	v_mov_b32_e32 v93, v23
	s_waitcnt lgkmcnt(0)
	v_add_f32_e32 v21, v21, v39
	ds_bpermute_b32 v39, v65, v21
	v_add_u32_e32 v20, s0, v20
	s_waitcnt lgkmcnt(0)
	v_add_f32_e32 v21, v21, v39
	ds_bpermute_b32 v39, v66, v21
	s_waitcnt lgkmcnt(0)
	v_add_f32_e32 v21, v21, v39
	ds_bpermute_b32 v39, v67, v21
	s_waitcnt lgkmcnt(0)
	v_add_f32_e32 v21, v21, v39
	ds_bpermute_b32 v39, v68, v21
	s_waitcnt lgkmcnt(0)
	v_add_f32_e32 v21, v21, v39
	ds_bpermute_b32 v39, v69, v21
	s_waitcnt lgkmcnt(0)
	v_add_f32_e32 v21, v21, v39
	v_fmamk_f32 v21, v21, 0x3a000000, v71
	v_mul_f32_e32 v39, 0x4b800000, v21
	v_cmp_gt_f32_e32 vcc, s1, v21
	s_nop 1
	v_cndmask_b32_e32 v21, v21, v39, vcc
	v_rsq_f32_e32 v21, v21
	s_nop 0
	v_mul_f32_e32 v39, 0x45800000, v21
	v_cndmask_b32_e32 v21, v21, v39, vcc
	v_mul_f32_e32 v39, v72, v21
	v_mul_f32_e32 v41, v73, v21
	v_mul_f32_e32 v43, v74, v21
	v_mul_f32_e32 v45, v75, v21
	v_mul_f32_e32 v39, v0, v39
	v_mul_f32_e32 v41, v1, v41
	v_mul_f32_e32 v43, v2, v43
	v_mul_f32_e32 v45, v3, v45
	v_cvt_pk_bf16_f32 v88, v39, v41
	v_cvt_pk_bf16_f32 v89, v43, v45
	s_load_dwordx2 s[16:17], s[6:7], 0xa8
	v_and_b32_e32 v39, 0x3fc0, v70
	v_lshlrev_b32_e32 v92, 1, v39
	v_mul_f32_e32 v39, v76, v21
	v_mul_f32_e32 v41, v77, v21
	s_waitcnt lgkmcnt(0)
	v_lshl_add_u64 v[76:77], s[16:17], 0, v[90:91]
	v_lshl_add_u64 v[76:77], v[76:77], 0, s[14:15]
	v_mul_f32_e32 v43, v78, v21
	v_mul_f32_e32 v45, v79, v21
	v_lshl_add_u64 v[78:79], v[76:77], 0, v[46:47]
	v_lshl_add_u64 v[78:79], v[78:79], 0, v[92:93]
	v_lshl_add_u64 v[78:79], v[78:79], 0, v[48:49]
	global_store_dwordx2 v[78:79], v[88:89], off
	v_mul_f32_e32 v18, v18, v21
	v_mul_f32_e32 v19, v19, v21
	v_mul_f32_e32 v14, v14, v21
	v_mul_f32_e32 v15, v15, v21
	v_mul_f32_e32 v10, v10, v21
	v_mul_f32_e32 v11, v11, v21
	v_cmp_lt_i32_e32 vcc, s3, v20
	v_add_u32_e32 v70, s38, v70
	s_or_b64 s[12:13], vcc, s[12:13]
	v_mul_f32_e32 v39, v144, v39
	v_mul_f32_e32 v41, v145, v41
	v_mul_f32_e32 v43, v146, v43
	v_mul_f32_e32 v45, v147, v45
	v_cvt_pk_bf16_f32 v78, v39, v41
	v_cvt_pk_bf16_f32 v79, v43, v45
	v_mul_f32_e32 v39, v80, v21
	v_mul_f32_e32 v41, v81, v21
	v_lshl_add_u64 v[80:81], v[76:77], 0, v[50:51]
	v_lshl_add_u64 v[80:81], v[80:81], 0, v[92:93]
	v_mul_f32_e32 v43, v82, v21
	v_mul_f32_e32 v45, v83, v21
	v_lshl_add_u64 v[80:81], v[80:81], 0, v[48:49]
	global_store_dwordx2 v[80:81], v[78:79], off
	v_lshl_add_u64 v[80:81], v[76:77], 0, v[52:53]
	v_lshl_add_u64 v[80:81], v[80:81], 0, v[92:93]
	v_lshl_add_u64 v[80:81], v[80:81], 0, v[48:49]
	v_mul_f32_e32 v39, v148, v39
	v_mul_f32_e32 v41, v149, v41
	v_mul_f32_e32 v43, v150, v43
	v_mul_f32_e32 v45, v151, v45
	v_cvt_pk_bf16_f32 v78, v39, v41
	v_cvt_pk_bf16_f32 v79, v43, v45
	v_mul_f32_e32 v39, v84, v21
	v_mul_f32_e32 v41, v85, v21
	v_mul_f32_e32 v43, v86, v21
	v_mul_f32_e32 v45, v87, v21
	global_store_dwordx2 v[80:81], v[78:79], off
	v_mul_f32_e32 v39, v39, v152
	v_mul_f32_e32 v41, v41, v153
	v_mul_f32_e32 v43, v43, v154
	v_mul_f32_e32 v45, v45, v155
	v_cvt_pk_bf16_f32 v78, v39, v41
	v_cvt_pk_bf16_f32 v79, v43, v45
	v_mul_f32_e32 v39, v16, v21
	v_mul_f32_e32 v41, v17, v21
	v_lshl_add_u64 v[16:17], v[76:77], 0, v[54:55]
	v_lshl_add_u64 v[16:17], v[16:17], 0, v[92:93]
	v_lshl_add_u64 v[16:17], v[16:17], 0, v[48:49]
	global_store_dwordx2 v[16:17], v[78:79], off
	v_mul_f32_e32 v16, v39, v156
	v_mul_f32_e32 v17, v41, v157
	v_mul_f32_e32 v18, v18, v158
	v_mul_f32_e32 v19, v19, v159
	v_cvt_pk_bf16_f32 v72, v16, v17
	v_cvt_pk_bf16_f32 v73, v18, v19
	v_mul_f32_e32 v39, v12, v21
	v_mul_f32_e32 v41, v13, v21
	v_lshl_add_u64 v[12:13], v[76:77], 0, v[56:57]
	v_lshl_add_u64 v[12:13], v[12:13], 0, v[92:93]
	v_lshl_add_u64 v[12:13], v[12:13], 0, v[48:49]
	global_store_dwordx2 v[12:13], v[72:73], off
	v_mul_f32_e32 v12, v39, v160
	v_mul_f32_e32 v13, v41, v161
	v_mul_f32_e32 v14, v14, v162
	v_mul_f32_e32 v15, v15, v163
	v_cvt_pk_bf16_f32 v16, v12, v13
	v_cvt_pk_bf16_f32 v17, v14, v15
	v_mul_f32_e32 v18, v8, v21
	v_mul_f32_e32 v19, v9, v21
	v_lshl_add_u64 v[8:9], v[76:77], 0, v[58:59]
	v_lshl_add_u64 v[8:9], v[8:9], 0, v[92:93]
	v_lshl_add_u64 v[8:9], v[8:9], 0, v[48:49]
	global_store_dwordx2 v[8:9], v[16:17], off
	v_mul_f32_e32 v16, v6, v21
	v_mul_f32_e32 v17, v7, v21
	v_lshl_add_u64 v[6:7], v[76:77], 0, v[62:63]
	v_lshl_add_u64 v[6:7], v[6:7], 0, v[92:93]
	v_lshl_add_u64 v[6:7], v[6:7], 0, v[48:49]
	v_mul_f32_e32 v8, v18, v164
	v_mul_f32_e32 v9, v19, v165
	v_mul_f32_e32 v10, v10, v166
	v_mul_f32_e32 v11, v11, v167
	v_cvt_pk_bf16_f32 v12, v8, v9
	v_cvt_pk_bf16_f32 v13, v10, v11
	v_mul_f32_e32 v14, v4, v21
	v_mul_f32_e32 v15, v5, v21
	v_lshl_add_u64 v[4:5], v[76:77], 0, v[60:61]
	v_lshl_add_u64 v[4:5], v[4:5], 0, v[92:93]
	v_lshl_add_u64 v[4:5], v[4:5], 0, v[48:49]
	global_store_dwordx2 v[4:5], v[12:13], off
	v_mul_f32_e32 v4, v14, v168
	v_mul_f32_e32 v5, v15, v169
	v_mul_f32_e32 v8, v16, v170
	v_mul_f32_e32 v9, v17, v171
	v_cvt_pk_bf16_f32 v4, v4, v5
	v_cvt_pk_bf16_f32 v5, v8, v9
	global_store_dwordx2 v[6:7], v[4:5], off
	s_andn2_b64 exec, exec, s[12:13]
	s_cbranch_execnz .LBB0_675

; __device__ __forceinline__ int mytid(int wv) { return (wv << 6) | (int)__builtin_amdgcn_mbcnt_hi(~0u, __builtin_amdgcn_mbcnt_lo(~0u, 0u)); }
; #define p getp()
; template <int MODE>
; __device__ __forceinline__ void rms_rows(KP p, const float* __restrict__ g, int wv) {
;   int tid = mytid(wv); asm volatile("" : "+v"(tid));
;   const int wid = tid >> 6, lane = tid & 63;
;   for (int row = blockIdx.x * 8 + wid; row < TOK; row += gridDim.x * 8) {
;     const float* src;
;     if (MODE == 0) src = (row < SEQ) ? p->x_prompt + (long)row * DM : p->x_sample + (long)(row - SEQ) * DM;
;     else src = p->X + (long)row * DM;
;     f32x4 v[8];
; #pragma unroll
;     for (int i = 0; i < 8; ++i) v[i] = *reinterpret_cast<const f32x4*>(src + (i * 64 + lane) * 4);
.LBB0_1018:
	s_or_b64 exec, exec, s[6:7]
	s_mov_b64 s[6:7], s[90:91]
	s_mov_b64 s[12:13], s[90:91]
	v_mov_b32_e32 v5, v192
	s_barrier
	v_readlane_b32 s0, v255, 8
	v_ashrrev_i32_e32 v4, 6, v5
	s_nop 0
	v_add_u32_e32 v20, s0, v4
	s_mov_b32 s0, 0xc000
	v_cmp_gt_i32_e32 vcc, s0, v20
	s_and_saveexec_b64 s[8:9], vcc
	s_cbranch_execz .LBB0_1021
	s_load_dwordx2 s[0:1], s[12:13], 0x18
	s_load_dwordx2 s[10:11], s[6:7], 0xa0
	v_lshlrev_b32_e32 v7, 2, v5
	v_and_b32_e32 v0, 64, v200
	v_and_b32_e32 v6, 0xfc, v7
	s_waitcnt lgkmcnt(0)
	s_add_u32 s12, s0, 0x2000
	v_add_u32_e32 v8, 64, v0
	s_addc_u32 s13, s1, 0
	v_lshlrev_b32_e32 v0, 2, v6
	global_load_dwordx4 v[0:3], v0, s[12:13]
	v_cmp_lt_i32_e32 vcc, v206, v8
	v_lshlrev_b32_e32 v5, 10, v5
	v_and_b32_e32 v18, 0xc000, v5
	v_cndmask_b32_e32 v9, v200, v206, vcc
	v_lshlrev_b32_e32 v64, 2, v9
	v_xor_b32_e32 v9, 16, v200
	v_cmp_lt_i32_e32 vcc, v9, v8
	v_mov_b32_e32 v23, 0
	v_or_b32_e32 v11, 0x300, v6
	v_cndmask_b32_e32 v9, v200, v9, vcc
	v_lshlrev_b32_e32 v65, 2, v9
	v_xor_b32_e32 v9, 8, v200
	v_cmp_lt_i32_e32 vcc, v9, v8
	v_or_b32_e32 v10, 0x400, v6
	v_or_b32_e32 v12, 0x500, v6
	v_cndmask_b32_e32 v9, v200, v9, vcc
	v_lshlrev_b32_e32 v66, 2, v9
	v_xor_b32_e32 v9, 4, v200
	v_cmp_lt_i32_e32 vcc, v9, v8
	v_or_b32_e32 v14, 0x600, v6
	v_or_b32_e32 v16, 0x700, v6
	v_cndmask_b32_e32 v9, v200, v9, vcc
	v_cmp_lt_i32_e32 vcc, v201, v8
	v_lshlrev_b32_e32 v67, 2, v9
	v_readlane_b32 s1, v255, 7
	v_cndmask_b32_e32 v9, v200, v201, vcc
	v_lshlrev_b32_e32 v68, 2, v9
	v_xor_b32_e32 v9, 1, v200
	v_cmp_lt_i32_e32 vcc, v9, v8
	s_lshl_b32 s0, s88, 3
	v_lshl_add_u32 v70, v4, 6, s1
	v_cndmask_b32_e32 v8, v200, v9, vcc
	v_lshlrev_b32_e32 v69, 2, v8
	v_and_b32_e32 v8, 60, v7
	v_or_b32_e32 v7, 0x100, v6
	v_or_b32_e32 v9, 0x200, v6
	v_lshlrev_b32_e32 v5, 8, v7
	v_lshlrev_b32_e32 v22, 2, v7
	v_and_b32_e32 v50, 0x1c000, v5
	v_lshlrev_b32_e32 v5, 8, v9
	v_lshl_add_u64 v[24:25], s[12:13], 0, v[22:23]
	v_lshlrev_b32_e32 v22, 2, v9
	v_and_b32_e32 v52, 0x2c000, v5
	v_lshlrev_b32_e32 v5, 8, v11
	v_lshl_add_u64 v[26:27], s[12:13], 0, v[22:23]
	v_lshlrev_b32_e32 v22, 2, v11
	v_and_b32_e32 v54, 0x3c000, v5
	v_lshlrev_b32_e32 v5, 8, v10
	v_lshl_add_u64 v[28:29], s[12:13], 0, v[22:23]
	v_lshlrev_b32_e32 v22, 2, v10
	v_and_b32_e32 v56, 0x4c000, v5
	v_lshlrev_b32_e32 v5, 8, v12
	v_lshl_add_u64 v[30:31], s[12:13], 0, v[22:23]
	v_lshlrev_b32_e32 v22, 2, v12
	v_and_b32_e32 v58, 0x5c000, v5
	v_lshlrev_b32_e32 v5, 8, v14
	v_lshl_add_u64 v[32:33], s[12:13], 0, v[22:23]
	v_lshlrev_b32_e32 v22, 2, v14
	v_and_b32_e32 v60, 0x6c000, v5
	v_lshlrev_b32_e32 v5, 8, v16
	v_lshl_add_u64 v[34:35], s[12:13], 0, v[22:23]
	v_lshlrev_b32_e32 v22, 2, v16
	v_and_b32_e32 v62, 0x7c000, v5
	v_lshl_add_u64 v[36:37], s[12:13], 0, v[22:23]
	s_mov_b64 s[12:13], 0
	v_lshlrev_b32_e32 v22, 2, v6
	v_lshlrev_b32_e32 v38, 2, v10
	v_lshlrev_b32_e32 v40, 2, v12
	v_lshlrev_b32_e32 v42, 2, v14
	v_lshlrev_b32_e32 v44, 2, v16
	v_mov_b32_e32 v71, 0x358637bd
	s_mov_b32 s1, 0x800000
	s_mov_b64 s[14:15], 0xba40000
	v_lshlrev_b32_e32 v46, 1, v18
	v_lshlrev_b32_e32 v48, 1, v8
	v_lshlrev_b32_e32 v50, 1, v50
	v_lshlrev_b32_e32 v52, 1, v52
	v_lshlrev_b32_e32 v54, 1, v54
	v_lshlrev_b32_e32 v56, 1, v56
	v_lshlrev_b32_e32 v58, 1, v58
	v_lshlrev_b32_e32 v60, 1, v60
	v_lshlrev_b32_e32 v62, 1, v62
	s_mov_b32 s3, 0xbfff
	global_load_dwordx4 v[144:147], v[24:25], off
	global_load_dwordx4 v[148:151], v[26:27], off
	global_load_dwordx4 v[152:155], v[28:29], off
	global_load_dwordx4 v[156:159], v[30:31], off
	global_load_dwordx4 v[160:163], v[32:33], off
	global_load_dwordx4 v[164:167], v[34:35], off
	global_load_dwordx4 v[168:171], v[36:37], off
